# attention K-loop: back edge rotated out of the compute segment's head (loop-back barrier is the loop head; exit path has its own barrier copy)
# baseline (speedup 1.0000x reference)
; __device__ __forceinline__ int v_st(int k, int c) { const int kk = (k & ~0xC) | ((k & 4) << 1) | ((k & 8) >> 1); return ((kk >> 3) * 4 + (c >> 5)) * 512 + ((kk & 7) * 32 + (c & 31)) * 2; }
; __device__ __forceinline__ int v_rd_base(int lane) { return ((lane & 3) << 3) | (((lane >> 2) & 3) << 6) | (((lane >> 4) & 1) << 5) | (((lane >> 5) & 1) << 8); }
; #define SLOAD(i, k0) do { sr_[i].vs0 = *(const bf16x8*)(&Vh[(long)((k0) + sr) * AT_LDK + sc]); sr_[i].vs1 = *(const bf16x8*)(&Vh[(long)((k0) + 32 + sr) * AT_LDK + sc]); \
;     sr_[i].ks0 = *(const bf16x8*)(&Kh[(long)((k0) + sr) * AT_LDK + sc]); sr_[i].ks1 = *(const bf16x8*)(&Kh[(long)((k0) + 32 + sr) * AT_LDK + sc]); } while (0)
; __device__ __forceinline__ void qkt(f32x16& p0, f32x16& p1, const char* Ks, const bf16x8* qr, int r32, int hi) {
; #pragma unroll
;   for (int r = 0; r < 16; ++r) { p0[r] = 0.f; p1[r] = 0.f; }
; #pragma unroll
;   for (int d0 = 0; d0 < 8; ++d0) { int cb = (d0 * 16 + hi * 8) * 2;
;     bf16x8 b0 = *reinterpret_cast<const bf16x8*>(Ks + KSWZ(r32, cb));
;     bf16x8 b1 = *reinterpret_cast<const bf16x8*>(Ks + KSWZ(32 + r32, cb));
;     p0 = __builtin_amdgcn_mfma_f32_32x32x16_bf16(b0, qr[d0], p0, 0, 0, 0);
;     p1 = __builtin_amdgcn_mfma_f32_32x32x16_bf16(b1, qr[d0], p1, 0, 0, 0); }
; }
; __device__ __forceinline__ void attn_dense_body(const u16* __restrict__ Qb, const u16* __restrict__ Kh, const u16* __restrict__ Vh,
;                                                 u16* __restrict__ Ob, int seq, char* lds, int tid) {
;     ...
;   const u16* Qw = Qb + (long)(wid * 32 + r32) * AT_LDQ + hi * 8;
; #pragma unroll
;   for (int d0 = 0; d0 < 8; ++d0) qr[d0] = *reinterpret_cast<const bf16x8*>(Qw + d0 * 16);
;   const int sr = tid >> 4, sc = (tid & 15) * 8, vst0 = v_st(sr, sc), vst1 = v_st(32 + sr, sc);
;   const int vb0 = (int)(uintptr_t)V_lds + v_rd_base(lane);
;   struct { bf16x8 vs0, vs1, ks0, ks1; } sr_[2];
;     ...
;   f32x16 pA0, pA1, pB0, pB1; float mnA, mnB, alA, alB; bf16x8 pa0, pa1, pa2, pa3; const int NT = seq / 64;
;   constexpr int SE = 0, SO = 1;
;   SLOAD(SE, 0); asm volatile("s_waitcnt vmcnt(0)" ::: "memory"); SWRITE(0, SE); __syncthreads();
;   qkt(pA0, pA1, K_lds, qr, r32, hi); partialSM(pA0, pA1, m_reg, mnA, alA);
.LBB0_189:
	s_lshr_b32 s0, s5, 2
	s_ashr_i32 s7, s6, 31
	s_mul_i32 s8, s6, 0xc00
	s_mul_hi_i32 s1, s6, 0xc00
	s_add_u32 s8, s92, s8
	s_addc_u32 s1, s93, s1
	s_lshl_b32 s55, s5, 7
	s_lshl_b32 s5, s5, 8
	s_add_u32 s8, s8, s5
	s_addc_u32 s9, s1, 0
	s_lshl_b32 s10, s4, 1
	s_add_i32 s10, s10, s0
	s_mul_i32 s0, s10, 0x110000
	v_readlane_b32 s4, v253, 13
	v_ashrrev_i32_e32 v16, 4, v180
	s_mul_hi_i32 s1, s10, 0x110000
	v_readlane_b32 s5, v253, 14
	s_add_u32 s4, s4, s0
	v_lshlrev_b32_e32 v22, 3, v180
	v_add_u32_e32 v18, 32, v16
	s_addc_u32 s5, s5, s1
	v_readlane_b32 s18, v253, 15
	v_and_b32_e32 v0, 0x78, v22
	v_ashrrev_i32_e32 v17, 31, v16
	v_ashrrev_i32_e32 v19, 31, v18
	v_readlane_b32 s19, v253, 16
	s_add_u32 s0, s18, s0
	v_lshlrev_b32_e32 v23, 1, v0
	v_lshlrev_b64 v[48:49], 8, v[16:17]
	v_lshlrev_b64 v[8:9], 8, v[18:19]
	s_addc_u32 s1, s19, s1
	v_or_b32_e32 v50, v48, v23
	v_mov_b32_e32 v51, v49
	v_or_b32_e32 v8, v8, v23
	s_waitcnt lgkmcnt(0)
	v_lshl_add_u64 v[0:1], s[0:1], 0, v[50:51]
	v_lshl_add_u64 v[4:5], s[0:1], 0, v[8:9]
	v_lshl_add_u64 v[10:11], s[4:5], 0, v[50:51]
	v_lshl_add_u64 v[12:13], s[4:5], 0, v[8:9]
	global_load_dwordx4 v[0:3], v[0:1], off
	s_nop 0
	global_load_dwordx4 v[4:7], v[4:5], off
	s_nop 0
	global_load_dwordx4 v[8:11], v[10:11], off
	s_nop 0
	global_load_dwordx4 v[12:15], v[12:13], off
	v_ashrrev_i32_e32 v52, 1, v180
	s_movk_i32 s11, 0xffe0
	v_bfe_u32 v181, v180, 5, 1
	v_bfi_b32 v17, s11, v52, v180
	v_mov_b64_e32 v[20:21], s[8:9]
	s_movk_i32 s8, 0xc00
	v_mad_i64_i32 v[20:21], s[8:9], v17, s8, v[20:21]
	v_lshlrev_b32_e32 v200, 4, v181
	v_lshl_add_u64 v[20:21], v[20:21], 0, v[200:201]
	global_load_dwordx4 v[116:119], v[20:21], off
	global_load_dwordx4 v[108:111], v[20:21], off offset:32
	global_load_dwordx4 v[124:127], v[20:21], off offset:64
	global_load_dwordx4 v[120:123], v[20:21], off offset:96
	global_load_dwordx4 v[112:115], v[20:21], off offset:128
	global_load_dwordx4 v[104:107], v[20:21], off offset:160
	global_load_dwordx4 v[100:103], v[20:21], off offset:192
	global_load_dwordx4 v[96:99], v[20:21], off offset:224
	v_and_b32_e32 v19, 0xfffff0, v16
	v_lshlrev_b32_e32 v24, 1, v16
	v_lshrrev_b32_e32 v25, 1, v16
	v_and_b32_e32 v26, 3, v16
	v_and_or_b32 v19, v24, 8, v19
	v_and_or_b32 v24, v25, 4, v26
	v_and_b32_e32 v25, 0xfffff0, v18
	v_lshlrev_b32_e32 v26, 1, v18
	v_and_b32_e32 v17, 0x70, v180
	v_bfe_u32 v22, v22, 5, 2
	v_lshlrev_b32_e32 v16, 8, v16
	v_lshlrev_b32_e32 v18, 8, v18
	v_lshrrev_b32_e32 v19, 1, v19
	v_and_or_b32 v25, v26, 8, v25
	v_bitop3_b32 v16, v23, v16, v17 bitop3:0xde
	v_bitop3_b32 v17, v23, v18, v17 bitop3:0xde
	v_or_b32_e32 v18, v19, v22
	v_lshrrev_b32_e32 v19, 1, v25
	v_lshlrev_b32_e32 v24, 6, v24
	v_and_b32_e32 v27, 48, v23
	v_add_u32_e32 v187, 0, v16
	v_add_u32_e32 v188, 0, v17
	v_lshlrev_b32_e32 v16, 9, v18
	v_or_b32_e32 v17, v19, v22
	v_or3_b32 v16, v16, v24, v27
	v_lshlrev_b32_e32 v17, 9, v17
	v_and_b32_e32 v182, 31, v180
	v_lshlrev_b32_e32 v53, 4, v180
	v_or3_b32 v17, v17, v24, v27
	v_add_u32_e32 v189, 0, v16
	v_add_u32_e32 v190, 0, v17
	s_waitcnt vmcnt(0)
	s_add_i32 s8, 0, 0x10000
	v_and_b32_e32 v176, 0xffffffe0, v52
	v_and_b32_e32 v74, 63, v180
	s_cmp_lg_u32 0, -1
	s_cselect_b32 s11, 0, 0
	s_mov_b32 s16, s17
	s_mov_b32 s18, s17
	s_waitcnt vmcnt(0)
	ds_write_b128 v189, v[0:3]
	s_waitcnt vmcnt(10)
	ds_write_b128 v190, v[4:7]
	s_waitcnt vmcnt(9)
	ds_write_b128 v187, v[8:11] offset:32768
	s_waitcnt vmcnt(8)
	ds_write_b128 v188, v[12:15] offset:32768
	v_lshlrev_b32_e32 v12, 8, v182
	v_and_b32_e32 v13, 0x70, v53
	v_bitop3_b32 v0, v200, v12, v13 bitop3:0xde
	v_add_u32_e32 v191, 0, v0
	s_waitcnt lgkmcnt(0)
	s_barrier
	ds_read_b128 v[0:3], v191 offset:32768
	ds_read_b128 v[4:7], v191 offset:40960
	s_waitcnt vmcnt(7) lgkmcnt(1)
	v_mfma_f32_32x32x16_bf16 v[16:31], v[0:3], v[116:119], 0
	v_or_b32_e32 v0, 32, v200
	v_bitop3_b32 v0, v0, v12, v13 bitop3:0xde
	v_add_u32_e32 v196, 0, v0
	v_and_b32_e32 v8, 0x3fffffc0, v180
	v_lshl_add_u32 v177, v8, 2, s8
	s_mov_b64 s[8:9], 0x4000
	v_and_b32_e32 v15, 0xc0, v53
	s_waitcnt lgkmcnt(0)
	v_mfma_f32_32x32x16_bf16 v[32:47], v[4:7], v[116:119], 0
	ds_read_b128 v[0:3], v196 offset:32768
	ds_read_b128 v[4:7], v196 offset:40960
	v_lshlrev_b32_e32 v14, 3, v74
	s_mov_b32 s19, s17
	s_mov_b32 s20, s17
	s_mov_b32 s21, s17
	s_mov_b32 s22, s17
	s_mov_b32 s23, s17
	s_waitcnt vmcnt(6) lgkmcnt(1)
	v_mfma_f32_32x32x16_bf16 v[16:31], v[0:3], v[108:111], v[16:31]
	v_or_b32_e32 v0, 64, v200
	v_bitop3_b32 v0, v0, v12, v13 bitop3:0xde
	v_add_u32_e32 v195, 0, v0
	s_mov_b32 s24, s17
	s_mov_b32 s25, s17
	s_mov_b32 s26, s17
	s_mov_b32 s27, s17
	s_waitcnt lgkmcnt(0)
	v_mfma_f32_32x32x16_bf16 v[32:47], v[4:7], v[108:111], v[32:47]
	ds_read_b128 v[0:3], v195 offset:32768
	ds_read_b128 v[4:7], v195 offset:40960
	s_mov_b32 s28, s17
	s_mov_b32 s29, s17
	s_mov_b32 s30, s17
	s_mov_b32 s31, s17
	v_lshl_add_u32 v183, v182, 2, v177
	v_mov_b32_e32 v184, 0
	s_waitcnt vmcnt(5) lgkmcnt(1)
	v_mfma_f32_32x32x16_bf16 v[16:31], v[0:3], v[124:127], v[16:31]
	v_or_b32_e32 v0, 0x60, v200
	v_bitop3_b32 v0, v0, v12, v13 bitop3:0xde
	v_add_u32_e32 v194, 0, v0
	s_waitcnt lgkmcnt(0)
	v_mfma_f32_32x32x16_bf16 v[32:47], v[4:7], v[124:127], v[32:47]
	ds_read_b128 v[0:3], v194 offset:32768
	ds_read_b128 v[4:7], v194 offset:40960
	s_waitcnt vmcnt(4) lgkmcnt(1)
	v_mfma_f32_32x32x16_bf16 v[16:31], v[0:3], v[120:123], v[16:31]
	v_or_b32_e32 v0, 0x80, v200
	v_bitop3_b32 v0, v0, v12, v13 bitop3:0xde
	v_add_u32_e32 v193, 0, v0
	s_waitcnt lgkmcnt(0)
	v_mfma_f32_32x32x16_bf16 v[32:47], v[4:7], v[120:123], v[32:47]
	ds_read_b128 v[0:3], v193 offset:32768
	ds_read_b128 v[4:7], v193 offset:40960
	s_waitcnt vmcnt(3) lgkmcnt(1)
; #define SLOAD(i, k0) do { sr_[i].vs0 = *(const bf16x8*)(&Vh[(long)((k0) + sr) * AT_LDK + sc]); sr_[i].vs1 = *(const bf16x8*)(&Vh[(long)((k0) + 32 + sr) * AT_LDK + sc]); \
;     sr_[i].ks0 = *(const bf16x8*)(&Kh[(long)((k0) + sr) * AT_LDK + sc]); sr_[i].ks1 = *(const bf16x8*)(&Kh[(long)((k0) + 32 + sr) * AT_LDK + sc]); } while (0)
; #define SWRITE(b, i) do { *(bf16x8*)(V_lds + (b) * SHM_V + vst0) = sr_[i].vs0;          \
;     *(bf16x8*)(V_lds + (b) * SHM_V + vst1) = sr_[i].vs1; int kc = sc * 2;               \
;     *(bf16x8*)(K_lds + (b) * SHM_K + KSWZ(sr, kc)) = sr_[i].ks0;                       \
;     *(bf16x8*)(K_lds + (b) * SHM_K + KSWZ(32 + sr, kc)) = sr_[i].ks1; } while (0)
; #define SWAIT() asm volatile("s_waitcnt vmcnt(4)" ::: "memory")
; __device__ __forceinline__ void partialSM(f32x16& p0, f32x16& p1, float& m_reg, float& mn, float& alpha) {
;   constexpr float C = AT_SCALE * 1.4426950408889634f;
;   float pmax = p0[0];
; #pragma unroll
;   for (int r = 1; r < 16; ++r) pmax = fmaxf(pmax, p0[r]);
; #pragma unroll
;   for (int r = 0; r < 16; ++r) pmax = fmaxf(pmax, p1[r]);
;   { auto rr = __builtin_amdgcn_permlane32_swap(__float_as_uint(pmax), __float_as_uint(pmax), false, false);
;     pmax = fmaxf(__uint_as_float(rr[0]), __uint_as_float(rr[1])); }
;   if (__builtin_expect(__all(pmax - m_reg <= AT_THR / AT_SCALE), 1)) { mn = m_reg; alpha = 1.f; }
;   else { mn = fmaxf(m_reg, pmax); alpha = __builtin_amdgcn_exp2f((m_reg - mn) * C); m_reg = mn; }
;   float mnC = -mn * C;
; #pragma unroll
;   for (int r = 0; r < 16; ++r) p0[r] = fmaf(p0[r], C, mnC);
; #pragma unroll
;   for (int r = 0; r < 16; ++r) p1[r] = fmaf(p1[r], C, mnC);
; #pragma unroll
;   for (int r = 0; r < 16; ++r) p0[r] = __builtin_amdgcn_exp2f(p0[r]);
; }
; __device__ __forceinline__ void attn_dense_body(const u16* __restrict__ Qb, const u16* __restrict__ Kh, const u16* __restrict__ Vh,
;                                                 u16* __restrict__ Ob, int seq, char* lds, int tid) {
;     ...
;   SLOAD(SE, 0); asm volatile("s_waitcnt vmcnt(0)" ::: "memory"); SWRITE(0, SE); __syncthreads();
;   qkt(pA0, pA1, K_lds, qr, r32, hi); partialSM(pA0, pA1, m_reg, mnA, alA);
;   SLOAD(SO, 64); if (2 < NT) SLOAD(SE, 2 * 64);
;   SWAIT(); SWRITE(1, SO); __syncthreads();
	v_mfma_f32_32x32x16_bf16 v[16:31], v[0:3], v[112:115], v[16:31]
	v_or_b32_e32 v0, 0xa0, v200
	v_bitop3_b32 v0, v0, v12, v13 bitop3:0xde
	v_add_u32_e32 v192, 0, v0
	ds_read_b128 v[0:3], v192 offset:32768
	s_waitcnt lgkmcnt(1)
	v_mfma_f32_32x32x16_bf16 v[32:47], v[4:7], v[112:115], v[32:47]
	ds_read_b128 v[4:7], v192 offset:40960
	s_waitcnt vmcnt(2) lgkmcnt(1)
	v_mfma_f32_32x32x16_bf16 v[16:31], v[0:3], v[104:107], v[16:31]
	v_lshl_add_u64 v[0:1], v[50:51], 0, s[8:9]
	s_mov_b64 s[8:9], 0x6000
	v_lshl_add_u64 v[2:3], s[0:1], 0, v[0:1]
	v_lshl_add_u64 v[8:9], v[50:51], 0, s[8:9]
	v_lshl_add_u64 v[0:1], s[4:5], 0, v[0:1]
	v_lshl_add_u64 v[10:11], s[0:1], 0, v[8:9]
	global_load_dwordx4 v[52:55], v[2:3], off
	global_load_dwordx4 v[56:59], v[10:11], off
	v_lshl_add_u64 v[2:3], s[4:5], 0, v[8:9]
	global_load_dwordx4 v[60:63], v[0:1], off
	global_load_dwordx4 v[64:67], v[2:3], off
	v_or_b32_e32 v0, 0xc0, v200
	v_bitop3_b32 v0, v0, v12, v13 bitop3:0xde
	v_add_u32_e32 v198, 0, v0
	ds_read_b128 v[0:3], v198 offset:32768
	v_lshlrev_b32_e32 v9, 1, v180
	v_and_or_b32 v8, v14, 24, v15
	s_waitcnt lgkmcnt(1)
	v_mfma_f32_32x32x16_bf16 v[32:47], v[4:7], v[104:107], v[32:47]
	v_and_b32_e32 v4, 32, v9
	v_and_b32_e32 v5, 0x100, v14
	v_or3_b32 v75, v8, v4, v5
	ds_read_b128 v[4:7], v198 offset:40960
	s_mov_b64 s[8:9], 0xa000
	v_add_u32_e32 v186, s11, v75
	s_waitcnt vmcnt(5) lgkmcnt(1)
	v_mfma_f32_32x32x16_bf16 v[16:31], v[0:3], v[100:103], v[16:31]
	v_or_b32_e32 v0, 0xe0, v200
	v_bitop3_b32 v0, v0, v12, v13 bitop3:0xde
	v_add_u32_e32 v197, 0, v0
	ds_read_b128 v[0:3], v197 offset:32768
	ds_read_b128 v[68:71], v197 offset:40960
	s_waitcnt lgkmcnt(2)
	v_mfma_f32_32x32x16_bf16 v[32:47], v[4:7], v[100:103], v[32:47]
	s_waitcnt vmcnt(4) lgkmcnt(1)
	v_mfma_f32_32x32x16_bf16 v[16:31], v[0:3], v[96:99], v[16:31]
	v_mov_b64_e32 v[0:1], s[16:17]
	v_mov_b64_e32 v[14:15], s[30:31]
	v_mov_b64_e32 v[2:3], s[18:19]
	v_mov_b64_e32 v[4:5], s[20:21]
	v_mov_b64_e32 v[6:7], s[22:23]
	v_mov_b64_e32 v[8:9], s[24:25]
	v_mov_b64_e32 v[10:11], s[26:27]
	s_waitcnt lgkmcnt(0)
	v_mfma_f32_32x32x16_bf16 v[32:47], v[68:71], v[96:99], v[32:47]
	s_nop 2
	v_max_f32_e32 v68, v17, v17
	v_max_f32_e32 v69, v16, v16
	v_max_f32_e32 v68, v69, v68
	v_max3_f32 v68, v68, v18, v19
	v_max3_f32 v68, v68, v20, v21
	v_max3_f32 v68, v68, v22, v23
	v_max3_f32 v68, v68, v24, v25
	v_max3_f32 v68, v68, v26, v27
	v_max3_f32 v68, v68, v28, v29
	v_max3_f32 v68, v68, v30, v31
	v_max3_f32 v68, v68, v32, v33
	v_max3_f32 v68, v68, v34, v35
	v_max3_f32 v68, v68, v36, v37
	v_max3_f32 v68, v68, v38, v39
	v_max3_f32 v68, v68, v40, v41
	v_max3_f32 v68, v68, v42, v43
	v_max3_f32 v76, v68, v44, v45
	v_lshl_add_u64 v[68:69], v[50:51], 0, s[8:9]
	v_lshl_add_u64 v[70:71], s[4:5], 0, v[68:69]
	v_lshl_add_u64 v[50:51], v[50:51], 0, s[90:91]
	v_lshl_add_u64 v[68:69], s[0:1], 0, v[68:69]
	v_lshl_add_u64 v[72:73], s[4:5], 0, v[50:51]
	global_load_dwordx4 v[136:139], v[70:71], off
	global_load_dwordx4 v[128:131], v[72:73], off
	v_lshl_add_u64 v[50:51], s[0:1], 0, v[50:51]
	global_load_dwordx4 v[140:143], v[68:69], off
	global_load_dwordx4 v[132:135], v[50:51], off
	v_max3_f32 v50, v76, v46, v47
	v_mov_b32_e32 v51, v50
	s_nop 1
	v_permlane32_swap_b32_e32 v50, v51
	v_max_f32_e32 v51, v51, v51
	v_max_f32_e32 v50, v50, v50
	v_max_f32_e32 v50, v50, v51
	v_add_f32_e32 v51, 0x7149f2ca, v50
	v_cmp_ge_f32_e32 vcc, s59, v51
	s_cmp_eq_u64 vcc, exec
	v_max_f32_e32 v51, 0xf149f2ca, v50
	s_cselect_b64 vcc, -1, 0
	v_mov_b32_e32 v50, 0xf149f2ca
	v_cndmask_b32_e32 v168, v51, v50, vcc
	v_mul_f32_e32 v50, 0xbe0293ee, v168
	v_fmamk_f32 v16, v16, 0x3e0293ee, v50
	v_exp_f32_e32 v161, v16
	v_fmamk_f32 v16, v17, 0x3e0293ee, v50
	v_exp_f32_e32 v175, v16
	v_fmamk_f32 v16, v18, 0x3e0293ee, v50
	v_exp_f32_e32 v162, v16
	v_fmamk_f32 v16, v19, 0x3e0293ee, v50
	v_exp_f32_e32 v212, v16
	v_fmamk_f32 v16, v20, 0x3e0293ee, v50
	v_exp_f32_e32 v174, v16
	v_fmamk_f32 v16, v21, 0x3e0293ee, v50
	v_exp_f32_e32 v215, v16
	v_fmamk_f32 v16, v22, 0x3e0293ee, v50
	v_exp_f32_e32 v163, v16
	v_fmamk_f32 v16, v23, 0x3e0293ee, v50
	v_exp_f32_e32 v173, v16
	v_fmamk_f32 v16, v24, 0x3e0293ee, v50
	v_exp_f32_e32 v164, v16
	v_fmamk_f32 v16, v25, 0x3e0293ee, v50
	v_exp_f32_e32 v171, v16
	v_fmamk_f32 v16, v26, 0x3e0293ee, v50
	v_exp_f32_e32 v165, v16
	v_fmamk_f32 v16, v27, 0x3e0293ee, v50
	v_exp_f32_e32 v172, v16
	v_fmamk_f32 v16, v28, 0x3e0293ee, v50
	v_pk_fma_f32 v[148:149], v[38:39], s[70:71], v[50:51] op_sel_hi:[1,0,0]
	v_sub_f32_e32 v38, 0xf149f2ca, v51
	v_exp_f32_e32 v166, v16
	v_fmamk_f32 v16, v29, 0x3e0293ee, v50
	v_mul_f32_e32 v38, 0x3e0293ee, v38
	v_exp_f32_e32 v169, v16
	v_fmamk_f32 v16, v30, 0x3e0293ee, v50
	v_exp_f32_e32 v38, v38
	v_exp_f32_e32 v167, v16
	v_mov_b32_e32 v16, 0x110000
	v_pk_fma_f32 v[144:145], v[46:47], s[70:71], v[50:51] op_sel_hi:[1,0,0]
	v_pk_fma_f32 v[150:151], v[44:45], s[70:71], v[50:51] op_sel_hi:[1,0,0]
	v_pk_fma_f32 v[154:155], v[42:43], s[70:71], v[50:51] op_sel_hi:[1,0,0]
	v_pk_fma_f32 v[146:147], v[40:41], s[70:71], v[50:51] op_sel_hi:[1,0,0]
	v_pk_fma_f32 v[152:153], v[36:37], s[70:71], v[50:51] op_sel_hi:[1,0,0]
	v_pk_fma_f32 v[156:157], v[34:35], s[70:71], v[50:51] op_sel_hi:[1,0,0]
	v_pk_fma_f32 v[158:159], v[32:33], s[70:71], v[50:51] op_sel_hi:[1,0,0]
	v_fmac_f32_e32 v50, 0x3e0293ee, v31
	v_mad_i64_i32 v[16:17], s[0:1], s10, v16, v[48:49]
	v_exp_f32_e32 v170, v50
	v_and_b32_e32 v18, 15, v180
	v_readlane_b32 s0, v254, 24
	s_waitcnt vmcnt(4)
	v_lshl_or_b32 v16, v18, 4, v16
	v_readlane_b32 s1, v254, 25
	v_mov_b64_e32 v[12:13], s[28:29]
	s_waitcnt vmcnt(7)
	ds_write_b128 v189, v[52:55] offset:16384
	s_waitcnt vmcnt(6)
	ds_write_b128 v190, v[56:59] offset:16384
	s_waitcnt vmcnt(5)
	ds_write_b128 v187, v[60:63] offset:49152
	s_waitcnt vmcnt(4)
	ds_write_b128 v188, v[64:67] offset:49152
	v_cndmask_b32_e64 v199, v38, 1.0, vcc
	s_addk_i32 s11, 0x4000
	v_lshl_add_u64 v[178:179], s[0:1], 0, v[16:17]
	v_mov_b64_e32 v[62:63], v[14:15]
	v_mov_b64_e32 v[46:47], v[14:15]
	v_mov_b64_e32 v[30:31], v[14:15]
	v_cmp_gt_u32_e64 s[4:5], 32, v74
	v_add_u32_e32 v185, s11, v75
	v_mov_b64_e32 v[60:61], v[12:13]
	v_mov_b64_e32 v[58:59], v[10:11]
	v_mov_b64_e32 v[56:57], v[8:9]
	v_mov_b64_e32 v[54:55], v[6:7]
	v_mov_b64_e32 v[52:53], v[4:5]
	v_mov_b64_e32 v[50:51], v[2:3]
	v_mov_b64_e32 v[48:49], v[0:1]
	v_mov_b64_e32 v[44:45], v[12:13]
	v_mov_b64_e32 v[42:43], v[10:11]
	v_mov_b64_e32 v[40:41], v[8:9]
	v_mov_b64_e32 v[38:39], v[6:7]
	v_mov_b64_e32 v[36:37], v[4:5]
	v_mov_b64_e32 v[34:35], v[2:3]
	v_mov_b64_e32 v[32:33], v[0:1]
	v_mov_b64_e32 v[28:29], v[12:13]
	v_mov_b64_e32 v[26:27], v[10:11]
	v_mov_b64_e32 v[24:25], v[8:9]
	v_mov_b64_e32 v[22:23], v[6:7]
	v_mov_b64_e32 v[20:21], v[4:5]
	v_mov_b64_e32 v[18:19], v[2:3]
	v_mov_b64_e32 v[16:17], v[0:1]
	s_waitcnt lgkmcnt(0)
; #define SBAR() __builtin_amdgcn_sched_barrier(0)
; #define SLOAD(i, k0) do { sr_[i].vs0 = *(const bf16x8*)(&Vh[(long)((k0) + sr) * AT_LDK + sc]); sr_[i].vs1 = *(const bf16x8*)(&Vh[(long)((k0) + 32 + sr) * AT_LDK + sc]); \
;     sr_[i].ks0 = *(const bf16x8*)(&Kh[(long)((k0) + sr) * AT_LDK + sc]); sr_[i].ks1 = *(const bf16x8*)(&Kh[(long)((k0) + 32 + sr) * AT_LDK + sc]); } while (0)
; __device__ __forceinline__ void attn_dense_body(const u16* __restrict__ Qb, const u16* __restrict__ Kh, const u16* __restrict__ Vh,
;                                                 u16* __restrict__ Ob, int seq, char* lds, int tid) {
;     ...
;   for (int j = 1; j + 1 < NT; j += 2) {
;     SBAR(); qkt(pB0, pB1, K_lds + SHM_K, qr, r32, hi);
;     finishSM(pA0, pA1, alA, l_reg, pa0, pa1, pa2, pa3); SBAR();
;     SLOAD(SO, (j + 2) * 64); SBAR();
;     pv_d0(o, vb0, pa0, pa1, pa2, pa3); partialSM(pB0, pB1, m_reg, mnB, alB);
.Latt_head:
	s_barrier
.LBB0_190:
	ds_read_b128 v[64:67], v191 offset:49152
	ds_read_b128 v[68:71], v191 offset:57344
	ds_read_b128 v[216:219], v196 offset:49152
	ds_read_b128 v[220:223], v196 offset:57344
	v_add_f32_e32 v160, 0, v161
	v_add_f32_e32 v160, v175, v160
	s_waitcnt lgkmcnt(3)
	v_mfma_f32_32x32x16_bf16 v[80:95], v[64:67], v[116:119], 0
	v_add_f32_e32 v160, v162, v160
	v_add_f32_e32 v160, v212, v160
	v_add_f32_e32 v160, v174, v160
	v_add_f32_e32 v160, v215, v160
	v_add_f32_e32 v160, v163, v160
	v_add_f32_e32 v160, v173, v160
	v_add_f32_e32 v160, v164, v160
	s_waitcnt lgkmcnt(2)
	v_mfma_f32_32x32x16_bf16 v[64:79], v[68:71], v[116:119], 0
	v_add_f32_e32 v160, v171, v160
	v_add_f32_e32 v160, v165, v160
	v_add_f32_e32 v160, v172, v160
	v_exp_f32_e32 v158, v158
	v_add_f32_e32 v160, v166, v160
	v_exp_f32_e32 v159, v159
	v_add_f32_e32 v160, v169, v160
	s_waitcnt lgkmcnt(1)
	v_mfma_f32_32x32x16_bf16 v[80:95], v[216:219], v[108:111], v[80:95]
	v_exp_f32_e32 v156, v156
	v_add_f32_e32 v160, v167, v160
	v_exp_f32_e32 v157, v157
	v_add_f32_e32 v160, v170, v160
	v_exp_f32_e32 v152, v152
	v_add_f32_e32 v160, v158, v160
	v_exp_f32_e32 v153, v153
	s_waitcnt lgkmcnt(0)
	v_mfma_f32_32x32x16_bf16 v[64:79], v[220:223], v[108:111], v[64:79]
	ds_read_b128 v[216:219], v195 offset:49152
	ds_read_b128 v[220:223], v195 offset:57344
	v_add_f32_e32 v160, v159, v160
	v_exp_f32_e32 v148, v148
	v_add_f32_e32 v160, v156, v160
	v_exp_f32_e32 v149, v149
	v_add_f32_e32 v160, v157, v160
	v_exp_f32_e32 v146, v146
	s_waitcnt lgkmcnt(1)
	v_mfma_f32_32x32x16_bf16 v[80:95], v[216:219], v[124:127], v[80:95]
	v_add_f32_e32 v160, v152, v160
	v_exp_f32_e32 v147, v147
	v_add_f32_e32 v160, v153, v160
	v_exp_f32_e32 v154, v154
	v_add_f32_e32 v160, v148, v160
	v_exp_f32_e32 v155, v155
	v_add_f32_e32 v160, v149, v160
	s_waitcnt lgkmcnt(0)
	v_mfma_f32_32x32x16_bf16 v[64:79], v[220:223], v[124:127], v[64:79]
	ds_read_b128 v[216:219], v194 offset:49152
	ds_read_b128 v[220:223], v194 offset:57344
	v_exp_f32_e32 v150, v150
	v_add_f32_e32 v160, v146, v160
	v_exp_f32_e32 v151, v151
	v_add_f32_e32 v160, v147, v160
	v_exp_f32_e32 v144, v144
	v_add_f32_e32 v160, v154, v160
	s_waitcnt lgkmcnt(1)
	v_mfma_f32_32x32x16_bf16 v[80:95], v[216:219], v[120:123], v[80:95]
	v_exp_f32_e32 v145, v145
	v_add_f32_e32 v160, v155, v160
	v_add_f32_e32 v160, v150, v160
	v_add_f32_e32 v160, v151, v160
	v_add_f32_e32 v160, v144, v160
	v_add_f32_e32 v209, v145, v160
	v_mov_b32_e32 v210, v209
	s_waitcnt lgkmcnt(0)
	v_mfma_f32_32x32x16_bf16 v[64:79], v[220:223], v[120:123], v[64:79]
	ds_read_b128 v[216:219], v193 offset:49152
	ds_read_b128 v[220:223], v193 offset:57344
	v_permlane32_swap_b32_e32 v209, v210
	s_waitcnt lgkmcnt(1)
	v_mfma_f32_32x32x16_bf16 v[80:95], v[216:219], v[112:115], v[80:95]
	s_waitcnt lgkmcnt(0)
	v_mfma_f32_32x32x16_bf16 v[64:79], v[220:223], v[112:115], v[64:79]
	ds_read_b128 v[216:219], v192 offset:49152
	ds_read_b128 v[220:223], v192 offset:57344
	s_waitcnt lgkmcnt(1)
	v_mfma_f32_32x32x16_bf16 v[80:95], v[216:219], v[104:107], v[80:95]
	s_waitcnt lgkmcnt(0)
	v_mfma_f32_32x32x16_bf16 v[64:79], v[220:223], v[104:107], v[64:79]
	ds_read_b128 v[216:219], v198 offset:49152
	ds_read_b128 v[220:223], v198 offset:57344
	s_waitcnt lgkmcnt(1)
	v_mfma_f32_32x32x16_bf16 v[80:95], v[216:219], v[100:103], v[80:95]
	s_waitcnt lgkmcnt(0)
	v_mfma_f32_32x32x16_bf16 v[64:79], v[220:223], v[100:103], v[64:79]
	ds_read_b128 v[216:219], v197 offset:49152
	ds_read_b128 v[220:223], v197 offset:57344
	v_cvt_pk_bf16_f32 v160, v161, v175
	v_cvt_pk_bf16_f32 v161, v162, v212
	v_cvt_pk_bf16_f32 v162, v174, v215
	v_cvt_pk_bf16_f32 v163, v163, v173
	v_cvt_pk_bf16_f32 v164, v164, v171
	v_cvt_pk_bf16_f32 v165, v165, v172
	s_waitcnt lgkmcnt(1)
	v_mfma_f32_32x32x16_bf16 v[80:95], v[216:219], v[96:99], v[80:95]
	v_permlane32_swap_b32_e32 v160, v162
	v_cvt_pk_bf16_f32 v166, v166, v169
	v_cvt_pk_bf16_f32 v167, v167, v170
	v_cvt_pk_bf16_f32 v170, v158, v159
	v_cvt_pk_bf16_f32 v171, v156, v157
	v_cvt_pk_bf16_f32 v172, v152, v153
	s_waitcnt lgkmcnt(0)
	v_mfma_f32_32x32x16_bf16 v[64:79], v[220:223], v[96:99], v[64:79]
	v_cvt_pk_bf16_f32 v173, v148, v149
	v_cvt_pk_bf16_f32 v212, v146, v147
	v_cvt_pk_bf16_f32 v213, v154, v155
	v_cvt_pk_bf16_f32 v214, v150, v151
	v_cvt_pk_bf16_f32 v215, v144, v145
	v_permlane32_swap_b32_e32 v161, v163
	v_permlane32_swap_b32_e32 v164, v166
	v_permlane32_swap_b32_e32 v165, v167
	v_permlane32_swap_b32_e32 v170, v172
	v_permlane32_swap_b32_e32 v171, v173
	v_permlane32_swap_b32_e32 v212, v214
	v_permlane32_swap_b32_e32 v213, v215
	s_movk_i32 s0, 0xa000
	v_add_co_u32_e32 v144, vcc, s0, v178
	s_movk_i32 s0, 0xc000
	s_nop 0
	v_addc_co_u32_e32 v145, vcc, -1, v179, vcc
	v_add_co_u32_e32 v148, vcc, s0, v178
	s_mov_b32 s0, 0xfeefa000
	s_nop 0
	v_addc_co_u32_e32 v149, vcc, -1, v179, vcc
	v_add_co_u32_e32 v152, vcc, s0, v178
	s_mov_b32 s0, 0xfeefc000
	s_nop 0
	v_addc_co_u32_e32 v153, vcc, -1, v179, vcc
	v_add_co_u32_e32 v156, vcc, s0, v178
	global_load_dwordx4 v[144:147], v[144:145], off
	s_nop 0
	global_load_dwordx4 v[148:151], v[148:149], off
	v_addc_co_u32_e32 v157, vcc, -1, v179, vcc
	global_load_dwordx4 v[152:155], v[152:153], off
	s_nop 0
	global_load_dwordx4 v[156:159], v[156:157], off
	ds_read_b64_tr_b16 v[216:217], v186 offset:0
	ds_read_b64_tr_b16 v[218:219], v186 offset:0x800
	ds_read_b64_tr_b16 v[220:221], v186 offset:0x1000
	ds_read_b64_tr_b16 v[222:223], v186 offset:0x1800
	ds_read_b64_tr_b16 v[224:225], v186 offset:0x2000
	ds_read_b64_tr_b16 v[226:227], v186 offset:0x2800
	ds_read_b64_tr_b16 v[228:229], v186 offset:0x3000
	ds_read_b64_tr_b16 v[230:231], v186 offset:0x3800
	s_waitcnt lgkmcnt(0)
; #define SBAR() __builtin_amdgcn_sched_barrier(0)
; template <int D0> __device__ __forceinline__ void pv_one(f32x16& od, int vb, bf16x8 pa0, bf16x8 pa1, bf16x8 pa2, bf16x8 pa3) {
;   const s16x4 l0 = tr_read<v_rd_off(D0, 0, 0)>(vb), h0 = tr_read<v_rd_off(D0, 0, 1)>(vb), l1 = tr_read<v_rd_off(D0, 1, 0)>(vb), h1 = tr_read<v_rd_off(D0, 1, 1)>(vb);
;   const s16x4 l2 = tr_read<v_rd_off(D0, 2, 0)>(vb), h2 = tr_read<v_rd_off(D0, 2, 1)>(vb), l3 = tr_read<v_rd_off(D0, 3, 0)>(vb), h3 = tr_read<v_rd_off(D0, 3, 1)>(vb);
;   asm volatile("s_waitcnt lgkmcnt(0)" ::: "memory"); SBAR();
;     ...
;   od = __builtin_amdgcn_mfma_f32_32x32x16_bf16(pa0, PK(l0, h0), od, 0, 0, 0);
;   od = __builtin_amdgcn_mfma_f32_32x32x16_bf16(pa1, PK(l1, h1), od, 0, 0, 0);
;   od = __builtin_amdgcn_mfma_f32_32x32x16_bf16(pa2, PK(l2, h2), od, 0, 0, 0);
;   od = __builtin_amdgcn_mfma_f32_32x32x16_bf16(pa3, PK(l3, h3), od, 0, 0, 0);
;     ...
; }
	s_nop 0
	v_mfma_f32_32x32x16_bf16 v[0:15], v[160:163], v[216:219], v[0:15]
	ds_read_b64_tr_b16 v[216:217], v186 offset:0x200
	ds_read_b64_tr_b16 v[218:219], v186 offset:0xa00
	v_mfma_f32_32x32x16_bf16 v[0:15], v[164:167], v[220:223], v[0:15]
	ds_read_b64_tr_b16 v[220:221], v186 offset:0x1200
	ds_read_b64_tr_b16 v[222:223], v186 offset:0x1a00
	v_mfma_f32_32x32x16_bf16 v[0:15], v[170:173], v[224:227], v[0:15]
	ds_read_b64_tr_b16 v[224:225], v186 offset:0x2200
	ds_read_b64_tr_b16 v[226:227], v186 offset:0x2a00
	v_mfma_f32_32x32x16_bf16 v[0:15], v[212:215], v[228:231], v[0:15]
	ds_read_b64_tr_b16 v[228:229], v186 offset:0x3200
	ds_read_b64_tr_b16 v[230:231], v186 offset:0x3a00
	s_waitcnt lgkmcnt(0)
	v_mfma_f32_32x32x16_bf16 v[48:63], v[160:163], v[216:219], v[48:63]
	ds_read_b64_tr_b16 v[216:217], v186 offset:0x400
	ds_read_b64_tr_b16 v[218:219], v186 offset:0xc00
	v_mfma_f32_32x32x16_bf16 v[48:63], v[164:167], v[220:223], v[48:63]
	ds_read_b64_tr_b16 v[220:221], v186 offset:0x1400
	ds_read_b64_tr_b16 v[222:223], v186 offset:0x1c00
	v_mfma_f32_32x32x16_bf16 v[48:63], v[170:173], v[224:227], v[48:63]
	ds_read_b64_tr_b16 v[224:225], v186 offset:0x2400
	ds_read_b64_tr_b16 v[226:227], v186 offset:0x2c00
	v_mfma_f32_32x32x16_bf16 v[48:63], v[212:215], v[228:231], v[48:63]
	ds_read_b64_tr_b16 v[228:229], v186 offset:0x3400
	ds_read_b64_tr_b16 v[230:231], v186 offset:0x3c00
	s_waitcnt lgkmcnt(0)
	v_mfma_f32_32x32x16_bf16 v[32:47], v[160:163], v[216:219], v[32:47]
	ds_read_b64_tr_b16 v[216:217], v186 offset:0x600
	ds_read_b64_tr_b16 v[218:219], v186 offset:0xe00
	v_mfma_f32_32x32x16_bf16 v[32:47], v[164:167], v[220:223], v[32:47]
	ds_read_b64_tr_b16 v[220:221], v186 offset:0x1600
	ds_read_b64_tr_b16 v[222:223], v186 offset:0x1e00
	v_mfma_f32_32x32x16_bf16 v[32:47], v[170:173], v[224:227], v[32:47]
	ds_read_b64_tr_b16 v[224:225], v186 offset:0x2600
	ds_read_b64_tr_b16 v[226:227], v186 offset:0x2e00
	v_mfma_f32_32x32x16_bf16 v[32:47], v[212:215], v[228:231], v[32:47]
	ds_read_b64_tr_b16 v[228:229], v186 offset:0x3600
	ds_read_b64_tr_b16 v[230:231], v186 offset:0x3e00
	s_waitcnt lgkmcnt(0)
	v_mfma_f32_32x32x16_bf16 v[16:31], v[160:163], v[216:219], v[16:31]
	v_max_f32_e32 v160, v81, v81
	v_max_f32_e32 v161, v80, v80
	v_max_f32_e32 v160, v161, v160
	v_max3_f32 v160, v160, v82, v83
	v_max3_f32 v160, v160, v84, v85
	v_max3_f32 v160, v160, v86, v87
	v_max3_f32 v160, v160, v88, v89
	v_max3_f32 v160, v160, v90, v91
	v_max3_f32 v160, v160, v92, v93
	v_mfma_f32_32x32x16_bf16 v[16:31], v[164:167], v[220:223], v[16:31]
	v_max3_f32 v160, v160, v94, v95
	v_max3_f32 v160, v160, v64, v65
	v_max3_f32 v160, v160, v66, v67
	v_max3_f32 v160, v160, v68, v69
	v_max3_f32 v160, v160, v70, v71
	v_max3_f32 v160, v160, v72, v73
	v_max3_f32 v160, v160, v74, v75
	v_max3_f32 v160, v160, v76, v77
	v_mfma_f32_32x32x16_bf16 v[16:31], v[170:173], v[224:227], v[16:31]
	v_max3_f32 v160, v160, v78, v79
	v_mov_b32_e32 v161, v160
	s_nop 1
	v_permlane32_swap_b32_e32 v160, v161
	v_max_f32_e32 v161, v161, v161
	v_max_f32_e32 v160, v160, v160
	v_max_f32_e32 v160, v160, v161
	v_sub_f32_e32 v161, v160, v168
	v_cmp_ge_f32_e32 vcc, s59, v161
	v_max_f32_e32 v161, v168, v168
	v_max_f32_e32 v160, v161, v160
	v_mfma_f32_32x32x16_bf16 v[16:31], v[212:215], v[228:231], v[16:31]
	v_sub_f32_e32 v161, v168, v160
	v_mul_f32_e32 v161, 0x3e0293ee, v161
	v_exp_f32_e32 v161, v161
	s_cmp_eq_u64 vcc, exec
	s_cselect_b64 s[0:1], -1, 0
	s_barrier
	s_waitcnt vmcnt(4)
	v_cndmask_b32_e64 v211, v161, 1.0, s[0:1]
	v_cmp_gt_f32_e32 vcc, 1.0, v211
	s_waitcnt vmcnt(4)
	ds_write_b128 v189, v[132:135]
	ds_write_b128 v190, v[140:143]
	ds_write_b128 v187, v[128:131] offset:32768
	ds_write_b128 v188, v[136:139] offset:32768
	s_cbranch_vccz .LBB0_194
	s_and_saveexec_b64 s[8:9], s[4:5]
	ds_write_b32 v183, v211 offset:128
	s_or_b64 exec, exec, s[8:9]
	s_waitcnt lgkmcnt(0)
	v_add_u32_e32 v161, v177, v200
	ds_read_b128 v[162:165], v161 offset:224
	ds_read_b128 v[170:173], v161 offset:192
	ds_read_b128 v[212:215], v161 offset:160
	ds_read_b128 v[216:219], v161 offset:128
	s_waitcnt lgkmcnt(3)
	v_pk_mul_f32 v[12:13], v[12:13], v[162:163]
	s_waitcnt lgkmcnt(2)
	v_pk_mul_f32 v[8:9], v[8:9], v[170:171]
	s_waitcnt lgkmcnt(1)
	v_pk_mul_f32 v[4:5], v[4:5], v[212:213]
	v_pk_mul_f32 v[14:15], v[14:15], v[164:165]
	v_pk_mul_f32 v[10:11], v[10:11], v[172:173]
	v_pk_mul_f32 v[6:7], v[6:7], v[214:215]
	s_waitcnt lgkmcnt(0)
	v_pk_mul_f32 v[2:3], v[2:3], v[218:219]
	v_pk_mul_f32 v[0:1], v[0:1], v[216:217]
	v_pk_mul_f32 v[60:61], v[60:61], v[162:163]
	v_pk_mul_f32 v[56:57], v[56:57], v[170:171]
	v_pk_mul_f32 v[52:53], v[52:53], v[212:213]
	v_pk_mul_f32 v[62:63], v[62:63], v[164:165]
	v_pk_mul_f32 v[58:59], v[58:59], v[172:173]
	v_pk_mul_f32 v[54:55], v[54:55], v[214:215]
	v_pk_mul_f32 v[50:51], v[50:51], v[218:219]
	v_pk_mul_f32 v[48:49], v[48:49], v[216:217]
	v_pk_mul_f32 v[44:45], v[44:45], v[162:163]
	v_pk_mul_f32 v[40:41], v[40:41], v[170:171]
	v_pk_mul_f32 v[36:37], v[36:37], v[212:213]
	v_pk_mul_f32 v[46:47], v[46:47], v[164:165]
	v_pk_mul_f32 v[42:43], v[42:43], v[172:173]
	v_pk_mul_f32 v[38:39], v[38:39], v[214:215]
	v_pk_mul_f32 v[34:35], v[34:35], v[218:219]
	v_pk_mul_f32 v[32:33], v[32:33], v[216:217]
	v_pk_mul_f32 v[28:29], v[28:29], v[162:163]
	v_pk_mul_f32 v[24:25], v[24:25], v[170:171]
	v_pk_mul_f32 v[20:21], v[20:21], v[212:213]
	v_pk_mul_f32 v[30:31], v[30:31], v[164:165]
	v_pk_mul_f32 v[26:27], v[26:27], v[172:173]
	v_pk_mul_f32 v[22:23], v[22:23], v[214:215]
	v_pk_mul_f32 v[18:19], v[18:19], v[218:219]
	v_pk_mul_f32 v[16:17], v[16:17], v[216:217]

; #define SBAR() __builtin_amdgcn_sched_barrier(0)
; __device__ __forceinline__ void partialSM(f32x16& p0, f32x16& p1, float& m_reg, float& mn, float& alpha) {
;     ...
;   float mnC = -mn * C;
; #pragma unroll
;   for (int r = 0; r < 16; ++r) p0[r] = fmaf(p0[r], C, mnC);
; #pragma unroll
;   for (int r = 0; r < 16; ++r) p1[r] = fmaf(p1[r], C, mnC);
; #pragma unroll
;   for (int r = 0; r < 16; ++r) p0[r] = __builtin_amdgcn_exp2f(p0[r]);
; }
; __device__ __forceinline__ void attn_dense_body(const u16* __restrict__ Qb, const u16* __restrict__ Kh, const u16* __restrict__ Vh,
;                                                 u16* __restrict__ Ob, int seq, char* lds, int tid) {
;     ...
;   SBAR(); qkt(pB0, pB1, K_lds + SHM_K, qr, r32, hi);
;   finishSM(pA0, pA1, alA, l_reg, pa0, pa1, pa2, pa3); SBAR();
;   pv_d0(o, vb0, pa0, pa1, pa2, pa3); partialSM(pB0, pB1, m_reg, mnB, alB);
.LBB0_200:
	v_cndmask_b32_e64 v168, v161, v212, s[0:1]
	v_mul_f32_e32 v144, 0xbe0293ee, v168
	v_mov_b32_e32 v145, v144
	v_fmamk_f32 v80, v80, 0x3e0293ee, v144
	v_fmamk_f32 v81, v81, 0x3e0293ee, v144
	v_fmamk_f32 v82, v82, 0x3e0293ee, v144
	v_fmamk_f32 v83, v83, 0x3e0293ee, v144
	v_fmamk_f32 v84, v84, 0x3e0293ee, v144
	v_fmamk_f32 v85, v85, 0x3e0293ee, v144
	v_fmamk_f32 v86, v86, 0x3e0293ee, v144
	v_fmamk_f32 v87, v87, 0x3e0293ee, v144
	v_fmamk_f32 v88, v88, 0x3e0293ee, v144
	v_fmamk_f32 v89, v89, 0x3e0293ee, v144
	v_fmamk_f32 v90, v90, 0x3e0293ee, v144
	v_fmamk_f32 v91, v91, 0x3e0293ee, v144
	v_fmamk_f32 v92, v92, 0x3e0293ee, v144
	v_fmamk_f32 v93, v93, 0x3e0293ee, v144
	v_fmamk_f32 v94, v94, 0x3e0293ee, v144
	v_fmac_f32_e32 v145, 0x3e0293ee, v95
	v_exp_f32_e32 v161, v80
	v_exp_f32_e32 v175, v81
	v_exp_f32_e32 v162, v82
	v_exp_f32_e32 v212, v83
	v_exp_f32_e32 v174, v84
	v_exp_f32_e32 v215, v85
	v_exp_f32_e32 v163, v86
	v_exp_f32_e32 v173, v87
	v_exp_f32_e32 v164, v88
	v_exp_f32_e32 v171, v89
	v_exp_f32_e32 v165, v90
	v_exp_f32_e32 v172, v91
	v_exp_f32_e32 v166, v92
	v_exp_f32_e32 v169, v93
	v_exp_f32_e32 v167, v94
	v_exp_f32_e32 v170, v145
	v_pk_fma_f32 v[158:159], v[64:65], s[70:71], v[144:145] op_sel_hi:[1,0,0]
	v_add_f32_e32 v64, v209, v210
	v_fmac_f32_e32 v64, v199, v184
	v_add_f32_e32 v184, v213, v214
	v_pk_fma_f32 v[156:157], v[66:67], s[70:71], v[144:145] op_sel_hi:[1,0,0]
	v_pk_fma_f32 v[152:153], v[68:69], s[70:71], v[144:145] op_sel_hi:[1,0,0]
	v_pk_fma_f32 v[148:149], v[70:71], s[70:71], v[144:145] op_sel_hi:[1,0,0]
	v_pk_fma_f32 v[146:147], v[72:73], s[70:71], v[144:145] op_sel_hi:[1,0,0]
	v_pk_fma_f32 v[154:155], v[74:75], s[70:71], v[144:145] op_sel_hi:[1,0,0]
	v_pk_fma_f32 v[150:151], v[76:77], s[70:71], v[144:145] op_sel_hi:[1,0,0]
	v_pk_fma_f32 v[144:145], v[78:79], s[70:71], v[144:145] op_sel_hi:[1,0,0]
	v_fmac_f32_e32 v184, v64, v211
	v_lshl_add_u64 v[178:179], v[178:179], 0, s[90:91]
	s_add_i32 s60, s60, 2
	s_and_b64 vcc, exec, s[8:9]
	s_waitcnt lgkmcnt(0)
	s_cbranch_vccnz .Latt_exit
	v_mov_b32_e32 v199, v160
	s_branch .Latt_head
.Latt_exit:
	s_barrier
.LBB0_202:
	ds_read_b128 v[64:67], v191 offset:49152
	ds_read_b128 v[68:71], v191 offset:57344
	s_waitcnt lgkmcnt(1)
	v_mfma_f32_32x32x16_bf16 v[80:95], v[64:67], v[116:119], 0
	s_waitcnt lgkmcnt(0)
	v_mfma_f32_32x32x16_bf16 v[64:79], v[68:71], v[116:119], 0
	ds_read_b128 v[116:119], v196 offset:49152
	ds_read_b128 v[128:131], v196 offset:57344
	s_waitcnt lgkmcnt(1)
	v_mfma_f32_32x32x16_bf16 v[80:95], v[116:119], v[108:111], v[80:95]
	s_waitcnt lgkmcnt(0)
	v_mfma_f32_32x32x16_bf16 v[64:79], v[128:131], v[108:111], v[64:79]
	ds_read_b128 v[108:111], v195 offset:49152
	ds_read_b128 v[116:119], v195 offset:57344
	s_waitcnt lgkmcnt(1)
	v_mfma_f32_32x32x16_bf16 v[80:95], v[108:111], v[124:127], v[80:95]
	s_waitcnt lgkmcnt(0)
	v_mfma_f32_32x32x16_bf16 v[64:79], v[116:119], v[124:127], v[64:79]
	ds_read_b128 v[108:111], v194 offset:49152
	ds_read_b128 v[116:119], v194 offset:57344
	s_waitcnt lgkmcnt(1)
	v_mfma_f32_32x32x16_bf16 v[80:95], v[108:111], v[120:123], v[80:95]
	s_waitcnt lgkmcnt(0)
	v_mfma_f32_32x32x16_bf16 v[64:79], v[116:119], v[120:123], v[64:79]
	ds_read_b128 v[108:111], v193 offset:49152
	ds_read_b128 v[116:119], v193 offset:57344
	v_exp_f32_e32 v120, v144
	v_exp_f32_e32 v121, v145
	s_waitcnt lgkmcnt(1)
	v_mfma_f32_32x32x16_bf16 v[80:95], v[108:111], v[112:115], v[80:95]
	s_waitcnt lgkmcnt(0)
	v_mfma_f32_32x32x16_bf16 v[64:79], v[116:119], v[112:115], v[64:79]
	ds_read_b128 v[108:111], v192 offset:49152
	ds_read_b128 v[112:115], v192 offset:57344
	v_exp_f32_e32 v116, v154
	v_exp_f32_e32 v117, v155
	v_exp_f32_e32 v118, v150
	v_exp_f32_e32 v119, v151
	s_waitcnt lgkmcnt(1)
	v_mfma_f32_32x32x16_bf16 v[80:95], v[108:111], v[104:107], v[80:95]
	s_waitcnt lgkmcnt(0)
	v_mfma_f32_32x32x16_bf16 v[64:79], v[112:115], v[104:107], v[64:79]
	ds_read_b128 v[104:107], v198 offset:49152
	ds_read_b128 v[108:111], v198 offset:57344
	v_exp_f32_e32 v112, v148
	v_exp_f32_e32 v113, v149
	v_exp_f32_e32 v114, v146
	v_exp_f32_e32 v115, v147
	s_waitcnt lgkmcnt(1)
	v_mfma_f32_32x32x16_bf16 v[80:95], v[104:107], v[100:103], v[80:95]
	s_waitcnt lgkmcnt(0)
	v_mfma_f32_32x32x16_bf16 v[64:79], v[108:111], v[100:103], v[64:79]
	ds_read_b128 v[100:103], v197 offset:49152
	ds_read_b128 v[104:107], v197 offset:57344
	v_exp_f32_e32 v108, v156
	v_exp_f32_e32 v109, v157
	v_exp_f32_e32 v110, v152
	v_exp_f32_e32 v111, v153
	s_waitcnt lgkmcnt(1)
	v_mfma_f32_32x32x16_bf16 v[80:95], v[100:103], v[96:99], v[80:95]
	s_waitcnt lgkmcnt(0)
; #define SBAR() __builtin_amdgcn_sched_barrier(0)
; __device__ __forceinline__ void finishSM(f32x16& p0, f32x16& p1, float alpha, float& l_reg, bf16x8& pa0, bf16x8& pa1, bf16x8& pa2, bf16x8& pa3) {
; #pragma unroll
;   for (int r = 0; r < 16; ++r) p1[r] = __builtin_amdgcn_exp2f(p1[r]);
;   float ps = 0;
; #pragma unroll
;   for (int r = 0; r < 16; ++r) ps += p0[r];
; #pragma unroll
;   for (int r = 0; r < 16; ++r) ps += p1[r];
;   { auto rr = __builtin_amdgcn_permlane32_swap(__float_as_uint(ps), __float_as_uint(ps), false, false);
;     ps = __uint_as_float(rr[0]) + __uint_as_float(rr[1]); }
;   l_reg = l_reg * alpha + ps;
;     ...
;   PK4(p0, 0, pa0); PK4(p0, 8, pa1); PK4(p1, 0, pa2); PK4(p1, 8, pa3);
;     ...
; }
; __device__ __forceinline__ void qkt(f32x16& p0, f32x16& p1, const char* Ks, const bf16x8* qr, int r32, int hi) {
; #pragma unroll
;   for (int r = 0; r < 16; ++r) { p0[r] = 0.f; p1[r] = 0.f; }
; #pragma unroll
;   for (int d0 = 0; d0 < 8; ++d0) { int cb = (d0 * 16 + hi * 8) * 2;
;     bf16x8 b0 = *reinterpret_cast<const bf16x8*>(Ks + KSWZ(r32, cb));
;     bf16x8 b1 = *reinterpret_cast<const bf16x8*>(Ks + KSWZ(32 + r32, cb));
;     p0 = __builtin_amdgcn_mfma_f32_32x32x16_bf16(b0, qr[d0], p0, 0, 0, 0);
;     p1 = __builtin_amdgcn_mfma_f32_32x32x16_bf16(b1, qr[d0], p1, 0, 0, 0); }
; }
; __device__ __forceinline__ int v_st(int k, int c) { const int kk = (k & ~0xC) | ((k & 4) << 1) | ((k & 8) >> 1); return ((kk >> 3) * 4 + (c >> 5)) * 512 + ((kk & 7) * 32 + (c & 31)) * 2; }
; __device__ __forceinline__ int v_rd_base(int lane) { return ((lane & 3) << 3) | (((lane >> 2) & 3) << 6) | (((lane >> 4) & 1) << 5) | (((lane >> 5) & 1) << 8); }
; template <int OFF> __device__ __forceinline__ s16x4 tr_read(int vb) {
;   s16x4 r; asm volatile("ds_read_b64_tr_b16 %0, %1 offset:%2" : "=&v"(r) : "v"(vb), "i"(OFF) : "memory"); return r;
; }
; template <int D0> __device__ __forceinline__ void pv_one(f32x16& od, int vb, bf16x8 pa0, bf16x8 pa1, bf16x8 pa2, bf16x8 pa3) {
;   const s16x4 l0 = tr_read<v_rd_off(D0, 0, 0)>(vb), h0 = tr_read<v_rd_off(D0, 0, 1)>(vb), l1 = tr_read<v_rd_off(D0, 1, 0)>(vb), h1 = tr_read<v_rd_off(D0, 1, 1)>(vb);
;   const s16x4 l2 = tr_read<v_rd_off(D0, 2, 0)>(vb), h2 = tr_read<v_rd_off(D0, 2, 1)>(vb), l3 = tr_read<v_rd_off(D0, 3, 0)>(vb), h3 = tr_read<v_rd_off(D0, 3, 1)>(vb);
;   asm volatile("s_waitcnt lgkmcnt(0)" ::: "memory"); SBAR();
	v_mfma_f32_32x32x16_bf16 v[64:79], v[104:107], v[96:99], v[64:79]
	v_add_f32_e32 v96, 0, v161
	v_add_f32_e32 v96, v175, v96
	v_add_f32_e32 v96, v162, v96
	v_add_f32_e32 v96, v212, v96
	v_add_f32_e32 v96, v174, v96
	v_add_f32_e32 v96, v215, v96
	v_add_f32_e32 v96, v163, v96
	v_add_f32_e32 v96, v173, v96
	v_add_f32_e32 v96, v164, v96
	v_add_f32_e32 v96, v171, v96
	v_add_f32_e32 v96, v165, v96
	v_add_f32_e32 v96, v172, v96
	v_exp_f32_e32 v106, v158
	v_add_f32_e32 v96, v166, v96
	v_exp_f32_e32 v107, v159
	v_add_f32_e32 v96, v169, v96
	v_add_f32_e32 v96, v167, v96
	v_add_f32_e32 v96, v170, v96
	v_add_f32_e32 v96, v106, v96
	v_add_f32_e32 v96, v107, v96
	v_add_f32_e32 v96, v108, v96
	v_add_f32_e32 v96, v109, v96
	v_add_f32_e32 v96, v110, v96
	v_add_f32_e32 v96, v111, v96
	v_add_f32_e32 v96, v112, v96
	v_add_f32_e32 v96, v113, v96
	v_add_f32_e32 v96, v114, v96
	v_add_f32_e32 v96, v115, v96
	v_add_f32_e32 v96, v116, v96
	v_add_f32_e32 v96, v117, v96
	v_add_f32_e32 v96, v118, v96
	v_add_f32_e32 v96, v119, v96
	v_add_f32_e32 v96, v120, v96
	v_add_f32_e32 v100, v121, v96
	v_mov_b32_e32 v101, v100
	v_cvt_pk_bf16_f32 v96, v161, v175
	v_cvt_pk_bf16_f32 v97, v162, v212
	v_cvt_pk_bf16_f32 v98, v174, v215
	v_cvt_pk_bf16_f32 v99, v163, v173
	s_nop 1
	v_permlane32_swap_b32_e32 v100, v101
	v_permlane32_swap_b32_e32 v96, v98
	v_permlane32_swap_b32_e32 v97, v99
	v_cvt_pk_bf16_f32 v102, v164, v171
	v_cvt_pk_bf16_f32 v103, v165, v172
	v_cvt_pk_bf16_f32 v104, v166, v169
	v_cvt_pk_bf16_f32 v105, v167, v170
	v_cvt_pk_bf16_f32 v106, v106, v107
	v_cvt_pk_bf16_f32 v107, v108, v109
	v_cvt_pk_bf16_f32 v108, v110, v111
	v_cvt_pk_bf16_f32 v109, v112, v113
	v_cvt_pk_bf16_f32 v110, v114, v115
	v_cvt_pk_bf16_f32 v111, v116, v117
	v_cvt_pk_bf16_f32 v112, v118, v119
	v_cvt_pk_bf16_f32 v113, v120, v121
	s_nop 0
	v_permlane32_swap_b32_e32 v102, v104
	v_permlane32_swap_b32_e32 v103, v105
	v_permlane32_swap_b32_e32 v106, v108
	v_permlane32_swap_b32_e32 v107, v109
	v_permlane32_swap_b32_e32 v110, v112
	v_permlane32_swap_b32_e32 v111, v113
	ds_read_b64_tr_b16 v[114:115], v186 offset:0
	ds_read_b64_tr_b16 v[116:117], v186 offset:0x800
	ds_read_b64_tr_b16 v[118:119], v186 offset:0x1000
	ds_read_b64_tr_b16 v[120:121], v186 offset:0x1800
	ds_read_b64_tr_b16 v[122:123], v186 offset:0x2000
	ds_read_b64_tr_b16 v[124:125], v186 offset:0x2800
	ds_read_b64_tr_b16 v[126:127], v186 offset:0x3000
	ds_read_b64_tr_b16 v[128:129], v186 offset:0x3800
	s_waitcnt lgkmcnt(0)
	s_nop 0
	v_mfma_f32_32x32x16_bf16 v[0:15], v[96:99], v[114:117], v[0:15]
	ds_read_b64_tr_b16 v[114:115], v186 offset:0x200
	ds_read_b64_tr_b16 v[116:117], v186 offset:0xa00
	v_mfma_f32_32x32x16_bf16 v[0:15], v[102:105], v[118:121], v[0:15]
	ds_read_b64_tr_b16 v[118:119], v186 offset:0x1200
	ds_read_b64_tr_b16 v[120:121], v186 offset:0x1a00
	v_mfma_f32_32x32x16_bf16 v[0:15], v[106:109], v[122:125], v[0:15]
	ds_read_b64_tr_b16 v[122:123], v186 offset:0x2200
	ds_read_b64_tr_b16 v[124:125], v186 offset:0x2a00
	v_mfma_f32_32x32x16_bf16 v[0:15], v[110:113], v[126:129], v[0:15]
	ds_read_b64_tr_b16 v[126:127], v186 offset:0x3200
	ds_read_b64_tr_b16 v[128:129], v186 offset:0x3a00
	s_waitcnt lgkmcnt(0)
	v_mfma_f32_32x32x16_bf16 v[48:63], v[96:99], v[114:117], v[48:63]
	ds_read_b64_tr_b16 v[114:115], v186 offset:0x400
	ds_read_b64_tr_b16 v[116:117], v186 offset:0xc00
	v_mfma_f32_32x32x16_bf16 v[48:63], v[102:105], v[118:121], v[48:63]
	ds_read_b64_tr_b16 v[118:119], v186 offset:0x1400
	ds_read_b64_tr_b16 v[120:121], v186 offset:0x1c00
	v_mfma_f32_32x32x16_bf16 v[48:63], v[106:109], v[122:125], v[48:63]
	ds_read_b64_tr_b16 v[122:123], v186 offset:0x2400
	ds_read_b64_tr_b16 v[124:125], v186 offset:0x2c00
	v_mfma_f32_32x32x16_bf16 v[48:63], v[110:113], v[126:129], v[48:63]
	ds_read_b64_tr_b16 v[126:127], v186 offset:0x3400
	ds_read_b64_tr_b16 v[128:129], v186 offset:0x3c00
	s_waitcnt lgkmcnt(0)
	v_mfma_f32_32x32x16_bf16 v[32:47], v[96:99], v[114:117], v[32:47]
	ds_read_b64_tr_b16 v[114:115], v186 offset:0x600
	ds_read_b64_tr_b16 v[116:117], v186 offset:0xe00
	v_mfma_f32_32x32x16_bf16 v[32:47], v[102:105], v[118:121], v[32:47]
	ds_read_b64_tr_b16 v[118:119], v186 offset:0x1600
	ds_read_b64_tr_b16 v[120:121], v186 offset:0x1e00
	v_mfma_f32_32x32x16_bf16 v[32:47], v[106:109], v[122:125], v[32:47]
	ds_read_b64_tr_b16 v[122:123], v186 offset:0x2600
	ds_read_b64_tr_b16 v[124:125], v186 offset:0x2e00
	v_mfma_f32_32x32x16_bf16 v[32:47], v[110:113], v[126:129], v[32:47]
	ds_read_b64_tr_b16 v[126:127], v186 offset:0x3600
	ds_read_b64_tr_b16 v[128:129], v186 offset:0x3e00
	s_waitcnt lgkmcnt(0)
	v_mfma_f32_32x32x16_bf16 v[16:31], v[96:99], v[114:117], v[16:31]
	v_max_f32_e32 v96, v81, v81
	v_max_f32_e32 v97, v80, v80
	v_max_f32_e32 v96, v97, v96
	v_max3_f32 v96, v96, v82, v83
	v_max3_f32 v96, v96, v84, v85
	v_max3_f32 v96, v96, v86, v87
	v_max3_f32 v96, v96, v88, v89
	v_max3_f32 v96, v96, v90, v91
	v_max3_f32 v96, v96, v92, v93
	v_mfma_f32_32x32x16_bf16 v[16:31], v[102:105], v[118:121], v[16:31]
	v_max3_f32 v96, v96, v94, v95
	v_max3_f32 v96, v96, v64, v65
	v_max3_f32 v96, v96, v66, v67
	v_max3_f32 v96, v96, v68, v69
	v_max3_f32 v96, v96, v70, v71
	v_max3_f32 v96, v96, v72, v73
	v_max3_f32 v96, v96, v74, v75
	v_max3_f32 v96, v96, v76, v77
	v_mfma_f32_32x32x16_bf16 v[16:31], v[106:109], v[122:125], v[16:31]
	v_max3_f32 v96, v96, v78, v79
	v_mov_b32_e32 v97, v96
	s_nop 1
	v_permlane32_swap_b32_e32 v96, v97
	v_max_f32_e32 v97, v97, v97
	v_max_f32_e32 v96, v96, v96
	v_max_f32_e32 v96, v96, v97
	v_sub_f32_e32 v97, v96, v168
	v_cmp_ge_f32_e32 vcc, s59, v97
	v_max_f32_e32 v97, v168, v168
	v_max_f32_e32 v97, v97, v96
	v_mfma_f32_32x32x16_bf16 v[16:31], v[110:113], v[126:129], v[16:31]
	v_sub_f32_e32 v96, v168, v97
	v_mul_f32_e32 v96, 0x3e0293ee, v96
	v_exp_f32_e32 v96, v96
	s_cmp_eq_u64 vcc, exec
	s_cselect_b64 s[0:1], -1, 0
	v_cndmask_b32_e64 v96, v96, 1.0, s[0:1]
	v_cmp_gt_f32_e32 vcc, 1.0, v96
	s_barrier
; #define RESC(a) do { if (__any((a) < 1.f)) { if (hi == 0) al_l[r32] = (a); asm volatile("s_waitcnt lgkmcnt(0)" ::: "memory"); \
;     for (int d = 0; d < 4; ++d) for (int r = 0; r < 16; ++r) o[d][r] *= al_l[crow(r, hi)]; } } while (0)
; __device__ __forceinline__ void attn_dense_body(const u16* __restrict__ Qb, const u16* __restrict__ Kh, const u16* __restrict__ Vh,
;                                                 u16* __restrict__ Ob, int seq, char* lds, int tid) {
;     ...
;   __syncthreads(); RESC(alB);
	s_cbranch_vccz .LBB0_206
	s_and_saveexec_b64 s[8:9], s[4:5]
	ds_write_b32 v183, v96 offset:128
	s_or_b64 exec, exec, s[8:9]
	s_waitcnt lgkmcnt(0)
	v_add_u32_e32 v98, v177, v200
	ds_read_b128 v[102:105], v98 offset:224
	ds_read_b128 v[106:109], v98 offset:192
	ds_read_b128 v[110:113], v98 offset:160
	ds_read_b128 v[114:117], v98 offset:128
	s_waitcnt lgkmcnt(3)
	v_pk_mul_f32 v[12:13], v[12:13], v[102:103]
	s_waitcnt lgkmcnt(2)
	v_pk_mul_f32 v[8:9], v[8:9], v[106:107]
	s_waitcnt lgkmcnt(1)
	v_pk_mul_f32 v[4:5], v[4:5], v[110:111]
	v_pk_mul_f32 v[14:15], v[14:15], v[104:105]
	v_pk_mul_f32 v[10:11], v[10:11], v[108:109]
	v_pk_mul_f32 v[6:7], v[6:7], v[112:113]
	s_waitcnt lgkmcnt(0)
	v_pk_mul_f32 v[2:3], v[2:3], v[116:117]
	v_pk_mul_f32 v[0:1], v[0:1], v[114:115]
	v_pk_mul_f32 v[60:61], v[60:61], v[102:103]
	v_pk_mul_f32 v[56:57], v[56:57], v[106:107]
	v_pk_mul_f32 v[52:53], v[52:53], v[110:111]
	v_pk_mul_f32 v[62:63], v[62:63], v[104:105]
	v_pk_mul_f32 v[58:59], v[58:59], v[108:109]
	v_pk_mul_f32 v[54:55], v[54:55], v[112:113]
	v_pk_mul_f32 v[50:51], v[50:51], v[116:117]
	v_pk_mul_f32 v[48:49], v[48:49], v[114:115]
	v_pk_mul_f32 v[44:45], v[44:45], v[102:103]
	v_pk_mul_f32 v[40:41], v[40:41], v[106:107]
	v_pk_mul_f32 v[36:37], v[36:37], v[110:111]
	v_pk_mul_f32 v[46:47], v[46:47], v[104:105]
	v_pk_mul_f32 v[42:43], v[42:43], v[108:109]
	v_pk_mul_f32 v[38:39], v[38:39], v[112:113]
	v_pk_mul_f32 v[34:35], v[34:35], v[116:117]
	v_pk_mul_f32 v[32:33], v[32:33], v[114:115]
	v_pk_mul_f32 v[28:29], v[28:29], v[102:103]
	v_pk_mul_f32 v[24:25], v[24:25], v[106:107]
	v_pk_mul_f32 v[20:21], v[20:21], v[110:111]
	v_pk_mul_f32 v[30:31], v[30:31], v[104:105]
	v_pk_mul_f32 v[26:27], v[26:27], v[108:109]
	v_pk_mul_f32 v[22:23], v[22:23], v[112:113]
	v_pk_mul_f32 v[18:19], v[18:19], v[116:117]
	v_pk_mul_f32 v[16:17], v[16:17], v[114:115]
